# nt hint on the read-once residual-stream (x) loads of the out-proj and FFN-down epilogues, on top of v033
# baseline (speedup 1.0000x reference)
;     __device__ __forceinline__ void operator()(const f32x4 (&acc)[2][2][4][2], const Unit& un, int wr, int wc, int fr_, int fq_) const {
;     ...
;         const int rbase = un.pm * 256 + wr * 64 + fr, cw = un.pn * 256 + wc * 32 + 8 * fq;
;         const bool lat = un.pm < (NLAT / 256);
;         const int slot = lat ? (un.pm >> 5) : 4;
;         const float* src = lat ? srcl : srcc; float* dst = lat ? dstl : dstc; const int radj = lat ? 0 : NLAT;
;         const float* gp = modg + (size_t)slot * 12288; const float* sp2 = sc2 + (size_t)slot * 12288;
;         float ssq[2][4];
; #pragma unroll
;         for (int ai = 0; ai < 2; ++ai)
; #pragma unroll
;             for (int m = 0; m < 4; ++m) ssq[ai][m] = 0.f;
;         f32x4 g0[2], g1[2], y0s[2], y1s[2];
; #pragma unroll
;         for (int bj = 0; bj < 2; ++bj) { const int col = cw + bj * 128; g0[bj] = *(const f32x4*)(gp + col); g1[bj] = *(const f32x4*)(gp + col + 4);
;             y0s[bj] = *(const f32x4*)(ng2 + col) * (*(const f32x4*)(sp2 + col) + 1.f); y1s[bj] = *(const f32x4*)(ng2 + col + 4) * (*(const f32x4*)(sp2 + col + 4) + 1.f); }
; #pragma unroll
;         for (int ai = 0; ai < 2; ++ai) {
;             f32x4 xa[4][2][2];
; #pragma unroll
;             for (int m = 0; m < 4; ++m)
; #pragma unroll
;                 for (int bj = 0; bj < 2; ++bj) { const float* sp = src + (size_t)(rbase + ai * 128 + m * 16 - radj) * D + cw + bj * 128; xa[m][bj][0] = *(const f32x4*)sp; xa[m][bj][1] = *(const f32x4*)(sp + 4); }
; #pragma unroll
;             for (int m = 0; m < 4; ++m)
; #pragma unroll
;                 for (int bj = 0; bj < 2; ++bj) { const int row = rbase + ai * 128 + m * 16, col = cw + bj * 128; const f32x4 v0 = acc[ai][bj][m][0], v1 = acc[ai][bj][m][1];
;                     float* dp = dst + (size_t)(row - radj) * D + col;
;                     const f32x4 x0 = xa[m][bj][0] + g0[bj] * v0, x1 = xa[m][bj][1] + g1[bj] * v1;
;                     *(f32x4*)dp = x0; *(f32x4*)(dp + 4) = x1;
;                     ssq[ai][m] += (x0.x * x0.x + x0.y * x0.y) + (x0.z * x0.z + x0.w * x0.w) + (x1.x * x1.x + x1.y * x1.y) + (x1.z * x1.z + x1.w * x1.w);
;                     const f32x4 y0 = x0 * y0s[bj], y1 = x1 * y1s[bj];
;                     u32x4 w; w.x = pk2(y0.x, y0.y); w.y = pk2(y0.z, y0.w); w.z = pk2(y1.x, y1.y); w.w = pk2(y1.z, y1.w); *(u32x4*)(xg + (size_t)row * D + col) = w; } }
.LBB0_1322:
	s_lshl_b32 s31, s40, 8
	s_add_i32 s31, s31, s64
	v_and_or_b32 v224, v211, 15, s31
	s_lshl_b32 s31, s38, 8
	s_or_b32 s31, s31, s65
	v_ashrrev_i32_e32 v116, 1, v211
	s_lshl_b64 s[40:41], s[46:47], 2
	v_and_b32_e32 v116, -8, v116
	s_add_u32 s46, s59, s40
	v_add_u32_e32 v248, s31, v116
	s_addc_u32 s47, s60, s41
	s_add_u32 s40, s61, s40
	v_ashrrev_i32_e32 v249, 31, v248
	s_addc_u32 s41, s62, s41
	v_lshlrev_b64 v[242:243], 2, v[248:249]
	v_lshl_add_u64 v[152:153], s[46:47], 0, v[242:243]
	v_lshl_add_u64 v[154:155], s[22:23], 0, v[242:243]
	v_lshl_add_u64 v[156:157], s[40:41], 0, v[242:243]
	global_load_dwordx4 v[128:131], v[152:153], off offset:16
	global_load_dwordx4 v[132:135], v[152:153], off
	global_load_dwordx4 v[116:119], v[154:155], off offset:16
	global_load_dwordx4 v[124:127], v[154:155], off
	global_load_dwordx4 v[144:147], v[156:157], off offset:16
	global_load_dwordx4 v[148:151], v[156:157], off
	v_subrev_u32_e32 v246, s29, v224
	v_ashrrev_i32_e32 v247, 31, v246
	v_lshl_add_u64 v[244:245], s[44:45], 0, v[242:243]
	v_lshlrev_b64 v[250:251], 13, v[246:247]
	v_lshl_add_u64 v[226:227], v[244:245], 0, v[250:251]
	global_load_dwordx4 v[200:203], v[226:227], off offset:16 nt
	global_load_dwordx4 v[204:207], v[226:227], off nt
	global_load_dwordx4 v[192:195], v[226:227], off offset:528 nt
	global_load_dwordx4 v[196:199], v[226:227], off offset:512 nt
	v_or_b32_e32 v228, 16, v246
	v_ashrrev_i32_e32 v229, 31, v228
	v_lshlrev_b64 v[228:229], 13, v[228:229]
	v_lshl_add_u64 v[228:229], v[244:245], 0, v[228:229]
	global_load_dwordx4 v[184:187], v[228:229], off offset:16 nt
	global_load_dwordx4 v[188:191], v[228:229], off nt
	global_load_dwordx4 v[176:179], v[228:229], off offset:528 nt
	global_load_dwordx4 v[180:183], v[228:229], off offset:512 nt
	v_or_b32_e32 v230, 32, v246
	v_ashrrev_i32_e32 v231, 31, v230
	v_lshlrev_b64 v[230:231], 13, v[230:231]
	v_lshl_add_u64 v[230:231], v[244:245], 0, v[230:231]
	global_load_dwordx4 v[168:171], v[230:231], off offset:16 nt
	global_load_dwordx4 v[172:175], v[230:231], off nt
	global_load_dwordx4 v[160:163], v[230:231], off offset:528 nt
	global_load_dwordx4 v[164:167], v[230:231], off offset:512 nt
	s_and_b64 vcc, exec, s[26:27]
	s_cbranch_vccz .LBB0_1319
	s_barrier
.LBB0_1319:
	v_ashrrev_i32_e32 v225, 31, v224
	v_lshlrev_b64 v[212:213], 12, v[224:225]
	s_ashr_i32 s39, s38, 31
	v_cmp_gt_u32_e32 vcc, 16, v211
	s_lshl_b64 s[38:39], s[38:39], 4
	s_waitcnt vmcnt(12)
	v_pk_add_f32 v[150:151], v[150:151], 1.0 op_sel_hi:[1,0]
	v_pk_add_f32 v[148:149], v[148:149], 1.0 op_sel_hi:[1,0]
	v_pk_mul_f32 v[234:235], v[126:127], v[150:151]
	v_pk_mul_f32 v[236:237], v[124:125], v[148:149]
	v_pk_add_f32 v[124:125], v[146:147], 1.0 op_sel_hi:[1,0]
	v_pk_add_f32 v[126:127], v[144:145], 1.0 op_sel_hi:[1,0]
	v_pk_mul_f32 v[238:239], v[118:119], v[124:125]
	v_pk_mul_f32 v[240:241], v[116:117], v[126:127]
	global_load_dwordx4 v[116:119], v[152:153], off offset:528
	global_load_dwordx4 v[124:127], v[152:153], off offset:512
	global_load_dwordx4 v[144:147], v[154:155], off offset:528
	global_load_dwordx4 v[148:151], v[154:155], off offset:512
	s_nop 0
	global_load_dwordx4 v[152:155], v[156:157], off offset:528
	s_nop 0
	global_load_dwordx4 v[156:159], v[156:157], off offset:512
	s_waitcnt vmcnt(0)
	v_pk_add_f32 v[158:159], v[158:159], 1.0 op_sel_hi:[1,0]
	s_nop 0
	v_pk_mul_f32 v[226:227], v[150:151], v[158:159]
	v_pk_add_f32 v[150:151], v[152:153], 1.0 op_sel_hi:[1,0]
	v_pk_add_f32 v[156:157], v[156:157], 1.0 op_sel_hi:[1,0]
	v_pk_mul_f32 v[232:233], v[144:145], v[150:151]
	v_or_b32_e32 v144, 48, v246
	v_ashrrev_i32_e32 v145, 31, v144
	v_pk_mul_f32 v[228:229], v[148:149], v[156:157]
	v_pk_add_f32 v[148:149], v[154:155], 1.0 op_sel_hi:[1,0]
	v_lshlrev_b64 v[144:145], 13, v[144:145]
	v_pk_mul_f32 v[230:231], v[146:147], v[148:149]
	v_lshl_add_u64 v[148:149], v[244:245], 0, v[144:145]
	global_load_dwordx4 v[152:155], v[148:149], off offset:16 nt
	global_load_dwordx4 v[156:159], v[148:149], off nt
	global_load_dwordx4 v[144:147], v[148:149], off offset:528 nt
	s_nop 0
	global_load_dwordx4 v[148:151], v[148:149], off offset:512 nt
	v_lshl_add_u64 v[250:251], s[42:43], 0, v[250:251]
	v_lshl_add_u64 v[250:251], v[250:251], 0, v[242:243]
	s_nop 0
	v_pk_fma_f32 v[136:137], v[136:137], v[128:129], v[200:201]
	s_nop 0
	v_pk_fma_f32 v[142:143], v[142:143], v[134:135], v[206:207]
	v_pk_fma_f32 v[140:141], v[140:141], v[132:133], v[204:205]
	v_mul_f32_e32 v201, v143, v143
	v_mul_f32_e32 v200, v141, v141
	v_fmac_f32_e32 v200, v140, v140
	v_fmac_f32_e32 v201, v142, v142
	v_add_f32_e32 v200, v200, v201
	v_mul_f32_e32 v201, v137, v137
	v_pk_fma_f32 v[138:139], v[138:139], v[130:131], v[202:203]
	v_fmac_f32_e32 v201, v136, v136
	v_add_f32_e32 v200, v200, v201
	v_mul_f32_e32 v201, v139, v139
	v_fmac_f32_e32 v201, v138, v138
	global_store_dwordx4 v[250:251], v[140:143], off
	global_store_dwordx4 v[250:251], v[136:139], off offset:16
	v_add_f32_e32 v202, v201, v200
	v_pk_mul_f32 v[140:141], v[236:237], v[140:141]
	v_pk_mul_f32 v[200:201], v[238:239], v[138:139]
	v_pk_mul_f32 v[138:139], v[240:241], v[136:137]
	v_pk_mul_f32 v[142:143], v[234:235], v[142:143]
	v_cvt_pk_bf16_f32 v136, v140, v141
	v_cvt_pk_bf16_f32 v138, v138, v139
	v_cvt_pk_bf16_f32 v139, v200, v201
	v_lshl_add_u64 v[140:141], s[20:21], 0, v[212:213]
	v_lshlrev_b64 v[200:201], 1, v[248:249]
	v_cvt_pk_bf16_f32 v137, v142, v143
	v_lshl_add_u64 v[140:141], v[140:141], 0, v[200:201]
	s_nop 0
	v_pk_fma_f32 v[122:123], v[122:123], v[126:127], v[198:199]
	v_pk_fma_f32 v[120:121], v[120:121], v[124:125], v[196:197]
	global_store_dwordx4 v[140:141], v[136:139], off
; __device__ __forceinline__ unsigned pk2(float lo, float hi) { const f32x2 v = {lo, hi}; return __builtin_bit_cast(unsigned, __builtin_convertvector(v, bf16x2_t)); }
;     __device__ __forceinline__ void operator()(const f32x4 (&acc)[2][2][4][2], const Unit& un, int wr, int wc, int fr_, int fq_) const {
;     ...
; #pragma unroll
;             for (int m = 0; m < 4; ++m)
; #pragma unroll
;                 for (int bj = 0; bj < 2; ++bj) { const int row = rbase + ai * 128 + m * 16, col = cw + bj * 128; const f32x4 v0 = acc[ai][bj][m][0], v1 = acc[ai][bj][m][1];
;                     float* dp = dst + (size_t)(row - radj) * D + col;
;                     const f32x4 x0 = xa[m][bj][0] + g0[bj] * v0, x1 = xa[m][bj][1] + g1[bj] * v1;
;                     *(f32x4*)dp = x0; *(f32x4*)(dp + 4) = x1;
;                     ssq[ai][m] += (x0.x * x0.x + x0.y * x0.y) + (x0.z * x0.z + x0.w * x0.w) + (x1.x * x1.x + x1.y * x1.y) + (x1.z * x1.z + x1.w * x1.w);
;                     const f32x4 y0 = x0 * y0s[bj], y1 = x1 * y1s[bj];
;                     u32x4 w; w.x = pk2(y0.x, y0.y); w.y = pk2(y0.z, y0.w); w.z = pk2(y1.x, y1.y); w.w = pk2(y1.z, y1.w); *(u32x4*)(xg + (size_t)row * D + col) = w; } }
	v_pk_fma_f32 v[112:113], v[112:113], v[116:117], v[192:193]
	v_pk_fma_f32 v[114:115], v[114:115], v[118:119], v[194:195]
	v_mul_f32_e32 v136, v121, v121
	v_mul_f32_e32 v137, v123, v123
	v_fmac_f32_e32 v136, v120, v120
	v_fmac_f32_e32 v137, v122, v122
	v_add_f32_e32 v136, v136, v137
	v_mul_f32_e32 v137, v113, v113
	v_fmac_f32_e32 v137, v112, v112
	v_add_f32_e32 v136, v136, v137
	v_mul_f32_e32 v137, v115, v115
	v_fmac_f32_e32 v137, v114, v114
	v_add_f32_e32 v136, v137, v136
	global_store_dwordx4 v[250:251], v[120:123], off offset:512
	global_store_dwordx4 v[250:251], v[112:115], off offset:528
	v_add_f32_e32 v194, v202, v136
	v_pk_mul_f32 v[122:123], v[226:227], v[122:123]
	v_pk_mul_f32 v[120:121], v[228:229], v[120:121]
	v_pk_mul_f32 v[136:137], v[230:231], v[114:115]
	v_pk_mul_f32 v[114:115], v[232:233], v[112:113]
	v_cvt_pk_bf16_f32 v112, v120, v121
	v_cvt_pk_bf16_f32 v113, v122, v123
	v_cvt_pk_bf16_f32 v114, v114, v115
	v_cvt_pk_bf16_f32 v115, v136, v137
	v_or_b32_e32 v192, 16, v224
	global_store_dwordx4 v[140:141], v[112:115], off offset:256
	v_ashrrev_i32_e32 v193, 31, v192
	v_lshlrev_b64 v[120:121], 12, v[192:193]
	v_subrev_u32_e32 v112, s29, v192
	v_ashrrev_i32_e32 v113, 31, v112
	v_lshlrev_b64 v[112:113], 13, v[112:113]
	v_lshl_add_u64 v[112:113], s[42:43], 0, v[112:113]
	s_nop 0
	v_pk_fma_f32 v[110:111], v[110:111], v[134:135], v[190:191]
	v_pk_fma_f32 v[108:109], v[108:109], v[132:133], v[188:189]
	v_pk_fma_f32 v[106:107], v[106:107], v[130:131], v[186:187]
	v_pk_fma_f32 v[104:105], v[104:105], v[128:129], v[184:185]
	v_lshl_add_u64 v[122:123], v[112:113], 0, v[242:243]
	v_pk_mul_f32 v[114:115], v[234:235], v[110:111]
	v_pk_mul_f32 v[112:113], v[236:237], v[108:109]
	v_pk_mul_f32 v[136:137], v[238:239], v[106:107]
	v_pk_mul_f32 v[138:139], v[240:241], v[104:105]
	v_lshl_add_u64 v[120:121], s[20:21], 0, v[120:121]
	v_cvt_pk_bf16_f32 v112, v112, v113
	v_cvt_pk_bf16_f32 v113, v114, v115
	v_cvt_pk_bf16_f32 v114, v138, v139
	v_cvt_pk_bf16_f32 v115, v136, v137
	v_lshl_add_u64 v[120:121], v[120:121], 0, v[200:201]
	s_nop 0
	v_pk_fma_f32 v[102:103], v[102:103], v[126:127], v[182:183]
	v_pk_fma_f32 v[100:101], v[100:101], v[124:125], v[180:181]
	v_pk_fma_f32 v[98:99], v[98:99], v[118:119], v[178:179]
	v_pk_fma_f32 v[96:97], v[96:97], v[116:117], v[176:177]
	global_store_dwordx4 v[122:123], v[108:111], off
	global_store_dwordx4 v[122:123], v[104:107], off offset:16
	global_store_dwordx4 v[120:121], v[112:115], off
	global_store_dwordx4 v[122:123], v[100:103], off offset:512
	global_store_dwordx4 v[122:123], v[96:99], off offset:528
	v_pk_mul_f32 v[114:115], v[226:227], v[102:103]
	v_pk_mul_f32 v[112:113], v[228:229], v[100:101]
	v_pk_mul_f32 v[122:123], v[230:231], v[98:99]
	v_pk_mul_f32 v[136:137], v[232:233], v[96:97]
	v_cvt_pk_bf16_f32 v112, v112, v113
	v_cvt_pk_bf16_f32 v113, v114, v115
	v_cvt_pk_bf16_f32 v114, v136, v137
	v_cvt_pk_bf16_f32 v115, v122, v123
	v_or_b32_e32 v176, 32, v224
	global_store_dwordx4 v[120:121], v[112:115], off offset:256
	v_ashrrev_i32_e32 v177, 31, v176
	v_lshlrev_b64 v[120:121], 12, v[176:177]
	v_subrev_u32_e32 v112, s29, v176
	v_ashrrev_i32_e32 v113, 31, v112
	v_lshlrev_b64 v[112:113], 13, v[112:113]
	v_lshl_add_u64 v[112:113], s[42:43], 0, v[112:113]
	s_nop 0
	v_pk_fma_f32 v[94:95], v[94:95], v[134:135], v[174:175]
	v_pk_fma_f32 v[92:93], v[92:93], v[132:133], v[172:173]
	v_pk_fma_f32 v[90:91], v[90:91], v[130:131], v[170:171]
	v_pk_fma_f32 v[88:89], v[88:89], v[128:129], v[168:169]
	v_lshl_add_u64 v[122:123], v[112:113], 0, v[242:243]
	v_pk_mul_f32 v[114:115], v[234:235], v[94:95]
	v_pk_mul_f32 v[112:113], v[236:237], v[92:93]
	v_pk_mul_f32 v[136:137], v[238:239], v[90:91]
	v_pk_mul_f32 v[138:139], v[240:241], v[88:89]
	v_lshl_add_u64 v[120:121], s[20:21], 0, v[120:121]
	v_cvt_pk_bf16_f32 v112, v112, v113
	v_cvt_pk_bf16_f32 v113, v114, v115
	v_cvt_pk_bf16_f32 v114, v138, v139
	v_cvt_pk_bf16_f32 v115, v136, v137
	v_lshl_add_u64 v[120:121], v[120:121], 0, v[200:201]
	s_nop 0
	v_pk_fma_f32 v[86:87], v[86:87], v[126:127], v[166:167]
	v_pk_fma_f32 v[84:85], v[84:85], v[124:125], v[164:165]
	v_pk_fma_f32 v[82:83], v[82:83], v[118:119], v[162:163]
	v_pk_fma_f32 v[80:81], v[80:81], v[116:117], v[160:161]
	global_store_dwordx4 v[122:123], v[92:95], off
	global_store_dwordx4 v[122:123], v[88:91], off offset:16
	global_store_dwordx4 v[120:121], v[112:115], off
	global_store_dwordx4 v[122:123], v[84:87], off offset:512
	global_store_dwordx4 v[122:123], v[80:83], off offset:528
	v_pk_mul_f32 v[114:115], v[226:227], v[86:87]
	v_pk_mul_f32 v[112:113], v[228:229], v[84:85]
	v_pk_mul_f32 v[122:123], v[230:231], v[82:83]
	v_pk_mul_f32 v[136:137], v[232:233], v[80:81]
	v_cvt_pk_bf16_f32 v112, v112, v113
	v_cvt_pk_bf16_f32 v113, v114, v115
	v_cvt_pk_bf16_f32 v114, v136, v137
	v_cvt_pk_bf16_f32 v115, v122, v123
	v_or_b32_e32 v160, 48, v224
	global_store_dwordx4 v[120:121], v[112:115], off offset:256
	v_ashrrev_i32_e32 v161, 31, v160
	v_lshlrev_b64 v[120:121], 12, v[160:161]
	v_subrev_u32_e32 v112, s29, v160
	v_ashrrev_i32_e32 v113, 31, v112
	v_lshlrev_b64 v[112:113], 13, v[112:113]
	v_lshl_add_u64 v[112:113], s[42:43], 0, v[112:113]
	s_waitcnt vmcnt(20)
	v_pk_fma_f32 v[78:79], v[78:79], v[134:135], v[158:159]
	v_pk_fma_f32 v[76:77], v[76:77], v[132:133], v[156:157]
	v_pk_fma_f32 v[74:75], v[74:75], v[130:131], v[154:155]
	v_pk_fma_f32 v[72:73], v[72:73], v[128:129], v[152:153]
	v_lshl_add_u64 v[122:123], v[112:113], 0, v[242:243]
	v_pk_mul_f32 v[114:115], v[234:235], v[78:79]
	v_pk_mul_f32 v[112:113], v[236:237], v[76:77]
	v_pk_mul_f32 v[136:137], v[238:239], v[74:75]
	v_pk_mul_f32 v[138:139], v[240:241], v[72:73]
	v_lshl_add_u64 v[120:121], s[20:21], 0, v[120:121]
	v_cvt_pk_bf16_f32 v112, v112, v113
	v_cvt_pk_bf16_f32 v113, v114, v115
	v_cvt_pk_bf16_f32 v114, v138, v139
	v_cvt_pk_bf16_f32 v115, v136, v137
	v_lshl_add_u64 v[120:121], v[120:121], 0, v[200:201]
	s_waitcnt vmcnt(18)
; __device__ __forceinline__ unsigned pk2(float lo, float hi) { const f32x2 v = {lo, hi}; return __builtin_bit_cast(unsigned, __builtin_convertvector(v, bf16x2_t)); }
;     __device__ __forceinline__ void operator()(const f32x4 (&acc)[2][2][4][2], const Unit& un, int wr, int wc, int fr_, int fq_) const {
;     ...
;         for (int ai = 0; ai < 2; ++ai) {
;             f32x4 xa[4][2][2];
; #pragma unroll
;             for (int m = 0; m < 4; ++m)
; #pragma unroll
;                 for (int bj = 0; bj < 2; ++bj) { const float* sp = src + (size_t)(rbase + ai * 128 + m * 16 - radj) * D + cw + bj * 128; xa[m][bj][0] = *(const f32x4*)sp; xa[m][bj][1] = *(const f32x4*)(sp + 4); }
; #pragma unroll
;             for (int m = 0; m < 4; ++m)
; #pragma unroll
;                 for (int bj = 0; bj < 2; ++bj) { const int row = rbase + ai * 128 + m * 16, col = cw + bj * 128; const f32x4 v0 = acc[ai][bj][m][0], v1 = acc[ai][bj][m][1];
;                     float* dp = dst + (size_t)(row - radj) * D + col;
;                     const f32x4 x0 = xa[m][bj][0] + g0[bj] * v0, x1 = xa[m][bj][1] + g1[bj] * v1;
;                     *(f32x4*)dp = x0; *(f32x4*)(dp + 4) = x1;
;                     ssq[ai][m] += (x0.x * x0.x + x0.y * x0.y) + (x0.z * x0.z + x0.w * x0.w) + (x1.x * x1.x + x1.y * x1.y) + (x1.z * x1.z + x1.w * x1.w);
;                     const f32x4 y0 = x0 * y0s[bj], y1 = x1 * y1s[bj];
;                     u32x4 w; w.x = pk2(y0.x, y0.y); w.y = pk2(y0.z, y0.w); w.z = pk2(y1.x, y1.y); w.w = pk2(y1.z, y1.w); *(u32x4*)(xg + (size_t)row * D + col) = w; } }
	v_pk_fma_f32 v[70:71], v[70:71], v[126:127], v[150:151]
	v_pk_fma_f32 v[68:69], v[68:69], v[124:125], v[148:149]
	v_pk_fma_f32 v[66:67], v[66:67], v[118:119], v[146:147]
	v_pk_fma_f32 v[64:65], v[64:65], v[116:117], v[144:145]
	global_store_dwordx4 v[122:123], v[76:79], off
	global_store_dwordx4 v[122:123], v[72:75], off offset:16
	global_store_dwordx4 v[120:121], v[112:115], off
	global_store_dwordx4 v[122:123], v[68:71], off offset:512
	global_store_dwordx4 v[122:123], v[64:67], off offset:528
	v_pk_mul_f32 v[114:115], v[226:227], v[70:71]
	v_pk_mul_f32 v[112:113], v[228:229], v[68:69]
	v_pk_mul_f32 v[122:123], v[230:231], v[66:67]
	v_pk_mul_f32 v[136:137], v[232:233], v[64:65]
	v_cvt_pk_bf16_f32 v112, v112, v113
	v_cvt_pk_bf16_f32 v113, v114, v115
	v_cvt_pk_bf16_f32 v114, v136, v137
	v_cvt_pk_bf16_f32 v115, v122, v123
	global_store_dwordx4 v[120:121], v[112:115], off offset:256
	v_add_u32_e32 v144, 0x80, v224
	v_subrev_u32_e32 v158, s29, v144
	v_add_u32_e32 v112, 0x80, v246
	v_ashrrev_i32_e32 v113, 31, v112
	v_lshlrev_b64 v[112:113], 13, v[112:113]
	v_lshl_add_u64 v[112:113], v[244:245], 0, v[112:113]
	global_load_dwordx4 v[146:149], v[112:113], off offset:16 nt
	global_load_dwordx4 v[150:153], v[112:113], off nt
	global_load_dwordx4 v[154:157], v[112:113], off offset:528 nt
	global_load_dwordx4 v[162:165], v[112:113], off offset:512 nt
	v_add_u32_e32 v112, 0x90, v246
	v_ashrrev_i32_e32 v113, 31, v112
	v_lshlrev_b64 v[112:113], 13, v[112:113]
	v_lshl_add_u64 v[112:113], v[244:245], 0, v[112:113]
	global_load_dwordx4 v[166:169], v[112:113], off offset:16 nt
	global_load_dwordx4 v[170:173], v[112:113], off nt
	global_load_dwordx4 v[178:181], v[112:113], off offset:528 nt
	global_load_dwordx4 v[182:185], v[112:113], off offset:512 nt
	v_add_u32_e32 v112, 0xa0, v246
	v_ashrrev_i32_e32 v113, 31, v112
	v_lshlrev_b64 v[112:113], 13, v[112:113]
	v_lshl_add_u64 v[112:113], v[244:245], 0, v[112:113]
	global_load_dwordx4 v[186:189], v[112:113], off offset:16 nt
	global_load_dwordx4 v[196:199], v[112:113], off nt
	global_load_dwordx4 v[202:205], v[112:113], off offset:528 nt
	global_load_dwordx4 v[248:251], v[112:113], off offset:512 nt
	v_add_u32_e32 v112, 0xb0, v246
	v_ashrrev_i32_e32 v113, 31, v112
	v_lshlrev_b64 v[112:113], 13, v[112:113]
	v_lshl_add_u64 v[120:121], v[244:245], 0, v[112:113]
	global_load_dwordx4 v[136:139], v[120:121], off offset:16 nt
	global_load_dwordx4 v[140:143], v[120:121], off nt
	global_load_dwordx4 v[112:115], v[120:121], off offset:528 nt
	s_nop 0
	global_load_dwordx4 v[120:123], v[120:121], off offset:512 nt
	v_ashrrev_i32_e32 v159, 31, v158
	v_ashrrev_i32_e32 v145, 31, v144
	v_lshlrev_b64 v[158:159], 13, v[158:159]
	v_lshlrev_b64 v[174:175], 12, v[144:145]
	v_lshl_add_u64 v[158:159], s[42:43], 0, v[158:159]
	v_lshl_add_u64 v[158:159], v[158:159], 0, v[242:243]
	s_waitcnt vmcnt(15)
	v_pk_fma_f32 v[58:59], v[58:59], v[130:131], v[148:149]
	s_waitcnt vmcnt(14)
	v_pk_fma_f32 v[62:63], v[62:63], v[134:135], v[152:153]
	v_pk_fma_f32 v[60:61], v[60:61], v[132:133], v[150:151]
	v_pk_fma_f32 v[56:57], v[56:57], v[128:129], v[146:147]
	v_pk_mul_f32 v[148:149], v[234:235], v[62:63]
	v_pk_mul_f32 v[146:147], v[236:237], v[60:61]
	v_pk_mul_f32 v[150:151], v[238:239], v[58:59]
	v_pk_mul_f32 v[152:153], v[240:241], v[56:57]
	v_cvt_pk_bf16_f32 v146, v146, v147
	v_cvt_pk_bf16_f32 v147, v148, v149
	v_cvt_pk_bf16_f32 v149, v150, v151
	v_lshl_add_u64 v[150:151], s[20:21], 0, v[174:175]
	v_cvt_pk_bf16_f32 v148, v152, v153
	v_lshl_add_u64 v[150:151], v[150:151], 0, v[200:201]
	s_waitcnt vmcnt(12)
	v_pk_fma_f32 v[54:55], v[54:55], v[126:127], v[164:165]
	v_pk_fma_f32 v[52:53], v[52:53], v[124:125], v[162:163]
	v_pk_fma_f32 v[50:51], v[50:51], v[118:119], v[156:157]
	v_pk_fma_f32 v[48:49], v[48:49], v[116:117], v[154:155]
	global_store_dwordx4 v[158:159], v[60:63], off
	global_store_dwordx4 v[158:159], v[56:59], off offset:16
	global_store_dwordx4 v[150:151], v[146:149], off
	v_pk_mul_f32 v[152:153], v[230:231], v[50:51]
	v_pk_mul_f32 v[154:155], v[232:233], v[48:49]
	v_pk_mul_f32 v[148:149], v[226:227], v[54:55]
	v_pk_mul_f32 v[146:147], v[228:229], v[52:53]
	global_store_dwordx4 v[158:159], v[52:55], off offset:512
	global_store_dwordx4 v[158:159], v[48:51], off offset:528
	v_cvt_pk_bf16_f32 v146, v146, v147
	v_cvt_pk_bf16_f32 v147, v148, v149
	v_cvt_pk_bf16_f32 v148, v154, v155
	v_cvt_pk_bf16_f32 v149, v152, v153
	global_store_dwordx4 v[150:151], v[146:149], off offset:256
	s_waitcnt vmcnt(16)
	v_pk_fma_f32 v[46:47], v[46:47], v[134:135], v[172:173]
	v_pk_fma_f32 v[44:45], v[44:45], v[132:133], v[170:171]
	v_add_u32_e32 v146, 0x90, v224
	v_subrev_u32_e32 v148, s29, v146
	v_ashrrev_i32_e32 v149, 31, v148
	v_lshlrev_b64 v[148:149], 13, v[148:149]
	v_ashrrev_i32_e32 v147, 31, v146
	v_lshl_add_u64 v[148:149], s[42:43], 0, v[148:149]
	v_lshlrev_b64 v[152:153], 12, v[146:147]
	v_pk_fma_f32 v[42:43], v[42:43], v[130:131], v[168:169]
	v_pk_fma_f32 v[40:41], v[40:41], v[128:129], v[166:167]
	v_lshl_add_u64 v[154:155], v[148:149], 0, v[242:243]
	v_pk_mul_f32 v[150:151], v[234:235], v[46:47]
	v_pk_mul_f32 v[148:149], v[236:237], v[44:45]
	v_pk_mul_f32 v[156:157], v[238:239], v[42:43]
	v_pk_mul_f32 v[158:159], v[240:241], v[40:41]
	v_lshl_add_u64 v[152:153], s[20:21], 0, v[152:153]
	v_cvt_pk_bf16_f32 v148, v148, v149
	v_cvt_pk_bf16_f32 v149, v150, v151
	v_cvt_pk_bf16_f32 v150, v158, v159
	v_cvt_pk_bf16_f32 v151, v156, v157
	v_lshl_add_u64 v[152:153], v[152:153], 0, v[200:201]
	s_waitcnt vmcnt(14)
; __device__ __forceinline__ unsigned pk2(float lo, float hi) { const f32x2 v = {lo, hi}; return __builtin_bit_cast(unsigned, __builtin_convertvector(v, bf16x2_t)); }
;     __device__ __forceinline__ void operator()(const f32x4 (&acc)[2][2][4][2], const Unit& un, int wr, int wc, int fr_, int fq_) const {
;     ...
; #pragma unroll
;             for (int m = 0; m < 4; ++m)
; #pragma unroll
;                 for (int bj = 0; bj < 2; ++bj) { const int row = rbase + ai * 128 + m * 16, col = cw + bj * 128; const f32x4 v0 = acc[ai][bj][m][0], v1 = acc[ai][bj][m][1];
;                     float* dp = dst + (size_t)(row - radj) * D + col;
;                     const f32x4 x0 = xa[m][bj][0] + g0[bj] * v0, x1 = xa[m][bj][1] + g1[bj] * v1;
;                     *(f32x4*)dp = x0; *(f32x4*)(dp + 4) = x1;
;                     ssq[ai][m] += (x0.x * x0.x + x0.y * x0.y) + (x0.z * x0.z + x0.w * x0.w) + (x1.x * x1.x + x1.y * x1.y) + (x1.z * x1.z + x1.w * x1.w);
;                     const f32x4 y0 = x0 * y0s[bj], y1 = x1 * y1s[bj];
;                     u32x4 w; w.x = pk2(y0.x, y0.y); w.y = pk2(y0.z, y0.w); w.z = pk2(y1.x, y1.y); w.w = pk2(y1.z, y1.w); *(u32x4*)(xg + (size_t)row * D + col) = w; } }
; #pragma unroll
;         for (int ai = 0; ai < 2; ++ai)
; #pragma unroll
;             for (int m = 0; m < 4; ++m) { float s = ssq[ai][m]; s += shx<16>(s); s += shx<32>(s);
;                 if (fq == 0) ps[((size_t)(rbase + ai * 128 + m * 16) * 8 + un.pn) * 4 + wc] = s; }
	v_pk_fma_f32 v[38:39], v[38:39], v[126:127], v[184:185]
	v_pk_fma_f32 v[36:37], v[36:37], v[124:125], v[182:183]
	v_pk_fma_f32 v[34:35], v[34:35], v[118:119], v[180:181]
	v_pk_fma_f32 v[32:33], v[32:33], v[116:117], v[178:179]
	global_store_dwordx4 v[154:155], v[44:47], off
	global_store_dwordx4 v[154:155], v[40:43], off offset:16
	global_store_dwordx4 v[152:153], v[148:151], off
	global_store_dwordx4 v[154:155], v[36:39], off offset:512
	global_store_dwordx4 v[154:155], v[32:35], off offset:528
	v_pk_mul_f32 v[150:151], v[226:227], v[38:39]
	v_pk_mul_f32 v[148:149], v[228:229], v[36:37]
	v_pk_mul_f32 v[154:155], v[230:231], v[34:35]
	v_pk_mul_f32 v[156:157], v[232:233], v[32:33]
	v_cvt_pk_bf16_f32 v148, v148, v149
	v_cvt_pk_bf16_f32 v149, v150, v151
	v_cvt_pk_bf16_f32 v150, v156, v157
	v_cvt_pk_bf16_f32 v151, v154, v155
	global_store_dwordx4 v[152:153], v[148:151], off offset:256
	s_waitcnt vmcnt(18)
	v_pk_fma_f32 v[30:31], v[30:31], v[134:135], v[198:199]
	v_pk_fma_f32 v[28:29], v[28:29], v[132:133], v[196:197]
	v_add_u32_e32 v148, 0xa0, v224
	v_subrev_u32_e32 v150, s29, v148
	v_ashrrev_i32_e32 v151, 31, v150
	v_lshlrev_b64 v[150:151], 13, v[150:151]
	v_ashrrev_i32_e32 v149, 31, v148
	v_lshl_add_u64 v[150:151], s[42:43], 0, v[150:151]
	v_lshlrev_b64 v[154:155], 12, v[148:149]
	v_pk_fma_f32 v[26:27], v[26:27], v[130:131], v[188:189]
	v_pk_fma_f32 v[24:25], v[24:25], v[128:129], v[186:187]
	v_lshl_add_u64 v[156:157], v[150:151], 0, v[242:243]
	v_pk_mul_f32 v[152:153], v[234:235], v[30:31]
	v_pk_mul_f32 v[150:151], v[236:237], v[28:29]
	v_pk_mul_f32 v[158:159], v[238:239], v[26:27]
	v_pk_mul_f32 v[162:163], v[240:241], v[24:25]
	v_lshl_add_u64 v[154:155], s[20:21], 0, v[154:155]
	v_cvt_pk_bf16_f32 v150, v150, v151
	v_cvt_pk_bf16_f32 v151, v152, v153
	v_cvt_pk_bf16_f32 v152, v162, v163
	v_cvt_pk_bf16_f32 v153, v158, v159
	v_lshl_add_u64 v[154:155], v[154:155], 0, v[200:201]
	s_waitcnt vmcnt(16)
	v_pk_fma_f32 v[22:23], v[22:23], v[126:127], v[250:251]
	v_pk_fma_f32 v[20:21], v[20:21], v[124:125], v[248:249]
	v_pk_fma_f32 v[18:19], v[18:19], v[118:119], v[204:205]
	v_pk_fma_f32 v[16:17], v[16:17], v[116:117], v[202:203]
	global_store_dwordx4 v[156:157], v[28:31], off
	global_store_dwordx4 v[156:157], v[24:27], off offset:16
	global_store_dwordx4 v[154:155], v[150:153], off
	global_store_dwordx4 v[156:157], v[20:23], off offset:512
	global_store_dwordx4 v[156:157], v[16:19], off offset:528
	v_pk_mul_f32 v[152:153], v[226:227], v[22:23]
	v_pk_mul_f32 v[150:151], v[228:229], v[20:21]
	v_pk_mul_f32 v[156:157], v[230:231], v[18:19]
	v_pk_mul_f32 v[158:159], v[232:233], v[16:17]
	v_cvt_pk_bf16_f32 v150, v150, v151
	v_cvt_pk_bf16_f32 v151, v152, v153
	v_cvt_pk_bf16_f32 v152, v158, v159
	v_cvt_pk_bf16_f32 v153, v156, v157
	global_store_dwordx4 v[154:155], v[150:153], off offset:256
	s_waitcnt vmcnt(20)
	v_pk_fma_f32 v[14:15], v[14:15], v[134:135], v[142:143]
	v_pk_fma_f32 v[12:13], v[12:13], v[132:133], v[140:141]
	v_add_u32_e32 v150, 0xb0, v224
	v_subrev_u32_e32 v152, s29, v150
	v_ashrrev_i32_e32 v153, 31, v152
	v_ashrrev_i32_e32 v151, 31, v150
	v_pk_fma_f32 v[10:11], v[10:11], v[130:131], v[138:139]
	v_lshlrev_b64 v[152:153], 13, v[152:153]
	v_lshlrev_b64 v[154:155], 12, v[150:151]
	v_pk_fma_f32 v[8:9], v[8:9], v[128:129], v[136:137]
	v_pk_mul_f32 v[130:131], v[234:235], v[14:15]
	v_pk_mul_f32 v[128:129], v[236:237], v[12:13]
	v_pk_mul_f32 v[132:133], v[238:239], v[10:11]
	s_waitcnt vmcnt(18)
	v_pk_fma_f32 v[6:7], v[6:7], v[126:127], v[122:123]
	v_pk_fma_f32 v[4:5], v[4:5], v[124:125], v[120:121]
	v_pk_fma_f32 v[2:3], v[2:3], v[118:119], v[114:115]
	v_pk_fma_f32 v[0:1], v[0:1], v[116:117], v[112:113]
	v_lshl_add_u64 v[152:153], s[42:43], 0, v[152:153]
	v_pk_mul_f32 v[134:135], v[240:241], v[8:9]
	v_cvt_pk_bf16_f32 v128, v128, v129
	v_cvt_pk_bf16_f32 v129, v130, v131
	v_cvt_pk_bf16_f32 v131, v132, v133
	v_lshl_add_u64 v[132:133], s[20:21], 0, v[154:155]
	v_pk_mul_f32 v[114:115], v[226:227], v[6:7]
	v_pk_mul_f32 v[112:113], v[228:229], v[4:5]
	v_pk_mul_f32 v[116:117], v[230:231], v[2:3]
	v_pk_mul_f32 v[118:119], v[232:233], v[0:1]
	v_lshl_add_u64 v[152:153], v[152:153], 0, v[242:243]
	v_cvt_pk_bf16_f32 v130, v134, v135
	v_lshl_add_u64 v[132:133], v[132:133], 0, v[200:201]
	v_cvt_pk_bf16_f32 v112, v112, v113
	v_cvt_pk_bf16_f32 v113, v114, v115
	v_cvt_pk_bf16_f32 v114, v118, v119
	v_cvt_pk_bf16_f32 v115, v116, v117
	global_store_dwordx4 v[152:153], v[12:15], off
	global_store_dwordx4 v[152:153], v[8:11], off offset:16
	global_store_dwordx4 v[132:133], v[128:131], off
	global_store_dwordx4 v[152:153], v[4:7], off offset:512
	global_store_dwordx4 v[152:153], v[0:3], off offset:528
	global_store_dwordx4 v[132:133], v[112:115], off offset:256
	ds_swizzle_b32 v112, v194 offset:swizzle(SWAP,16)
	s_nop 0
	v_mbcnt_lo_u32_b32 v113, -1, 0
	v_mbcnt_hi_u32_b32 v113, -1, v113
	s_waitcnt lgkmcnt(0)
	v_add_f32_e32 v112, v194, v112
	v_lshlrev_b32_e32 v113, 2, v113
	v_xor_b32_e32 v113, 0x80, v113
	ds_bpermute_b32 v113, v113, v112
	s_and_saveexec_b64 s[40:41], vcc
	s_mov_b32 s74, 0x240000
	s_cbranch_execz .LBB0_1324
	v_lshlrev_b64 v[114:115], 7, v[224:225]
	v_lshl_add_u64 v[114:115], s[24:25], 0, v[114:115]
	v_lshl_add_u64 v[114:115], v[114:115], 0, s[38:39]
	s_mov_b32 s43, s91
	s_lshl_b32 s42, s63, 2
	v_lshl_add_u64 v[114:115], v[114:115], 0, s[42:43]
	s_waitcnt lgkmcnt(0)
	v_add_f32_e32 v112, v112, v113
	global_store_dword v[114:115], v112, off

;     __device__ __forceinline__ void operator()(const f32x4 (&acc)[2][2][4][2], const Unit& un, int wr, int wc, int fr_, int fq_) const {
;     ...
;         const int rbase = un.pm * 256 + wr * 64 + fr, cw = un.pn * 256 + wc * 32 + 8 * fq;
;         const bool lat = un.pm < (NLAT / 256);
;         const int slot = lat ? (un.pm >> 5) : 4;
;         const float* src = lat ? srcl : srcc; float* dst = lat ? dstl : dstc; const int radj = lat ? 0 : NLAT;
;         const float* gp = modg + (size_t)slot * 12288; const float* sp2 = sc2 + (size_t)slot * 12288;
;         float ssq[2][4];
; #pragma unroll
;         for (int ai = 0; ai < 2; ++ai)
; #pragma unroll
;             for (int m = 0; m < 4; ++m) ssq[ai][m] = 0.f;
;         f32x4 g0[2], g1[2], y0s[2], y1s[2];
; #pragma unroll
;         for (int bj = 0; bj < 2; ++bj) { const int col = cw + bj * 128; g0[bj] = *(const f32x4*)(gp + col); g1[bj] = *(const f32x4*)(gp + col + 4);
;             y0s[bj] = *(const f32x4*)(ng2 + col) * (*(const f32x4*)(sp2 + col) + 1.f); y1s[bj] = *(const f32x4*)(ng2 + col + 4) * (*(const f32x4*)(sp2 + col + 4) + 1.f); }
; #pragma unroll
;         for (int ai = 0; ai < 2; ++ai) {
;             f32x4 xa[4][2][2];
; #pragma unroll
;             for (int m = 0; m < 4; ++m)
; #pragma unroll
;                 for (int bj = 0; bj < 2; ++bj) { const float* sp = src + (size_t)(rbase + ai * 128 + m * 16 - radj) * D + cw + bj * 128; xa[m][bj][0] = *(const f32x4*)sp; xa[m][bj][1] = *(const f32x4*)(sp + 4); }
; #pragma unroll
;             for (int m = 0; m < 4; ++m)
; #pragma unroll
;                 for (int bj = 0; bj < 2; ++bj) { const int row = rbase + ai * 128 + m * 16, col = cw + bj * 128; const f32x4 v0 = acc[ai][bj][m][0], v1 = acc[ai][bj][m][1];
;                     float* dp = dst + (size_t)(row - radj) * D + col;
;                     const f32x4 x0 = xa[m][bj][0] + g0[bj] * v0, x1 = xa[m][bj][1] + g1[bj] * v1;
;                     *(f32x4*)dp = x0; *(f32x4*)(dp + 4) = x1;
;                     ssq[ai][m] += (x0.x * x0.x + x0.y * x0.y) + (x0.z * x0.z + x0.w * x0.w) + (x1.x * x1.x + x1.y * x1.y) + (x1.z * x1.z + x1.w * x1.w);
;                     const f32x4 y0 = x0 * y0s[bj], y1 = x1 * y1s[bj];
;                     u32x4 w; w.x = pk2(y0.x, y0.y); w.y = pk2(y0.z, y0.w); w.z = pk2(y1.x, y1.y); w.w = pk2(y1.z, y1.w); *(u32x4*)(xg + (size_t)row * D + col) = w; } }
.LBB0_1565:
	s_lshl_b32 s31, s40, 8
	s_add_i32 s31, s31, s64
	v_and_or_b32 v224, v211, 15, s31
	s_lshl_b32 s31, s38, 8
	s_or_b32 s31, s31, s65
	v_ashrrev_i32_e32 v116, 1, v211
	s_lshl_b64 s[40:41], s[46:47], 2
	v_and_b32_e32 v116, -8, v116
	s_add_u32 s46, s59, s40
	v_add_u32_e32 v248, s31, v116
	s_addc_u32 s47, s60, s41
	s_add_u32 s40, s61, s40
	v_ashrrev_i32_e32 v249, 31, v248
	s_addc_u32 s41, s62, s41
	v_lshlrev_b64 v[242:243], 2, v[248:249]
	v_lshl_add_u64 v[152:153], s[46:47], 0, v[242:243]
	v_lshl_add_u64 v[154:155], s[22:23], 0, v[242:243]
	v_lshl_add_u64 v[156:157], s[40:41], 0, v[242:243]
	global_load_dwordx4 v[128:131], v[152:153], off offset:16
	global_load_dwordx4 v[132:135], v[152:153], off
	global_load_dwordx4 v[116:119], v[154:155], off offset:16
	global_load_dwordx4 v[124:127], v[154:155], off
	global_load_dwordx4 v[144:147], v[156:157], off offset:16
	global_load_dwordx4 v[148:151], v[156:157], off
	v_subrev_u32_e32 v246, s29, v224
	v_ashrrev_i32_e32 v247, 31, v246
	v_lshl_add_u64 v[244:245], s[44:45], 0, v[242:243]
	v_lshlrev_b64 v[212:213], 13, v[246:247]
	v_lshl_add_u64 v[226:227], v[244:245], 0, v[212:213]
	global_load_dwordx4 v[200:203], v[226:227], off offset:16 nt
	global_load_dwordx4 v[204:207], v[226:227], off nt
	global_load_dwordx4 v[192:195], v[226:227], off offset:528 nt
	global_load_dwordx4 v[196:199], v[226:227], off offset:512 nt
	v_or_b32_e32 v228, 16, v246
	v_ashrrev_i32_e32 v229, 31, v228
	v_lshlrev_b64 v[228:229], 13, v[228:229]
	v_lshl_add_u64 v[228:229], v[244:245], 0, v[228:229]
	global_load_dwordx4 v[184:187], v[228:229], off offset:16 nt
	global_load_dwordx4 v[188:191], v[228:229], off nt
	global_load_dwordx4 v[176:179], v[228:229], off offset:528 nt
	global_load_dwordx4 v[180:183], v[228:229], off offset:512 nt
	v_or_b32_e32 v230, 32, v246
	v_ashrrev_i32_e32 v231, 31, v230
	v_lshlrev_b64 v[230:231], 13, v[230:231]
	v_lshl_add_u64 v[230:231], v[244:245], 0, v[230:231]
	global_load_dwordx4 v[168:171], v[230:231], off offset:16 nt
	global_load_dwordx4 v[172:175], v[230:231], off nt
	global_load_dwordx4 v[160:163], v[230:231], off offset:528 nt
	global_load_dwordx4 v[164:167], v[230:231], off offset:512 nt
	s_and_b64 vcc, exec, s[26:27]
	s_cbranch_vccz .LBB0_1562
	s_barrier
.LBB0_1562:
	v_ashrrev_i32_e32 v225, 31, v224
	v_lshlrev_b64 v[250:251], 12, v[224:225]
	s_ashr_i32 s39, s38, 31
	v_cmp_gt_u32_e32 vcc, 16, v211
	s_lshl_b64 s[38:39], s[38:39], 4
	s_waitcnt vmcnt(12)
	v_pk_add_f32 v[150:151], v[150:151], 1.0 op_sel_hi:[1,0]
	v_pk_add_f32 v[148:149], v[148:149], 1.0 op_sel_hi:[1,0]
	v_pk_mul_f32 v[234:235], v[126:127], v[150:151]
	v_pk_mul_f32 v[236:237], v[124:125], v[148:149]
	v_pk_add_f32 v[124:125], v[146:147], 1.0 op_sel_hi:[1,0]
	v_pk_add_f32 v[126:127], v[144:145], 1.0 op_sel_hi:[1,0]
	v_pk_mul_f32 v[238:239], v[118:119], v[124:125]
	v_pk_mul_f32 v[240:241], v[116:117], v[126:127]
	global_load_dwordx4 v[116:119], v[152:153], off offset:528
	global_load_dwordx4 v[124:127], v[152:153], off offset:512
	global_load_dwordx4 v[144:147], v[154:155], off offset:528
	global_load_dwordx4 v[148:151], v[154:155], off offset:512
	s_nop 0
	global_load_dwordx4 v[152:155], v[156:157], off offset:528
	s_nop 0
	global_load_dwordx4 v[156:159], v[156:157], off offset:512
	s_waitcnt vmcnt(0)
	v_pk_add_f32 v[158:159], v[158:159], 1.0 op_sel_hi:[1,0]
	s_nop 0
	v_pk_mul_f32 v[226:227], v[150:151], v[158:159]
	v_pk_add_f32 v[150:151], v[152:153], 1.0 op_sel_hi:[1,0]
	v_pk_add_f32 v[156:157], v[156:157], 1.0 op_sel_hi:[1,0]
	v_pk_mul_f32 v[232:233], v[144:145], v[150:151]
	v_or_b32_e32 v144, 48, v246
	v_ashrrev_i32_e32 v145, 31, v144
	v_pk_mul_f32 v[228:229], v[148:149], v[156:157]
	v_pk_add_f32 v[148:149], v[154:155], 1.0 op_sel_hi:[1,0]
	v_lshlrev_b64 v[144:145], 13, v[144:145]
	v_pk_mul_f32 v[230:231], v[146:147], v[148:149]
	v_lshl_add_u64 v[148:149], v[244:245], 0, v[144:145]
	global_load_dwordx4 v[152:155], v[148:149], off offset:16 nt
	global_load_dwordx4 v[156:159], v[148:149], off nt
	global_load_dwordx4 v[144:147], v[148:149], off offset:528 nt
	s_nop 0
	global_load_dwordx4 v[148:151], v[148:149], off offset:512 nt
	v_lshl_add_u64 v[212:213], s[42:43], 0, v[212:213]
	v_lshl_add_u64 v[212:213], v[212:213], 0, v[242:243]
	s_nop 0
	v_pk_fma_f32 v[136:137], v[136:137], v[128:129], v[200:201]
	s_nop 0
	v_pk_fma_f32 v[142:143], v[142:143], v[134:135], v[206:207]
	v_pk_fma_f32 v[140:141], v[140:141], v[132:133], v[204:205]
	v_mul_f32_e32 v201, v143, v143
	v_mul_f32_e32 v200, v141, v141
	v_fmac_f32_e32 v200, v140, v140
	v_fmac_f32_e32 v201, v142, v142
	v_add_f32_e32 v200, v200, v201
	v_mul_f32_e32 v201, v137, v137
	v_pk_fma_f32 v[138:139], v[138:139], v[130:131], v[202:203]
	v_fmac_f32_e32 v201, v136, v136
	v_add_f32_e32 v200, v200, v201
	v_mul_f32_e32 v201, v139, v139
	v_fmac_f32_e32 v201, v138, v138
	global_store_dwordx4 v[212:213], v[140:143], off
	global_store_dwordx4 v[212:213], v[136:139], off offset:16
	v_add_f32_e32 v202, v201, v200
	v_pk_mul_f32 v[140:141], v[236:237], v[140:141]
	v_pk_mul_f32 v[200:201], v[238:239], v[138:139]
	v_pk_mul_f32 v[138:139], v[240:241], v[136:137]
	v_pk_mul_f32 v[142:143], v[234:235], v[142:143]
	v_cvt_pk_bf16_f32 v136, v140, v141
	v_cvt_pk_bf16_f32 v138, v138, v139
	v_cvt_pk_bf16_f32 v139, v200, v201
	v_lshl_add_u64 v[140:141], s[20:21], 0, v[250:251]
	v_lshlrev_b64 v[200:201], 1, v[248:249]
	v_cvt_pk_bf16_f32 v137, v142, v143
	v_lshl_add_u64 v[140:141], v[140:141], 0, v[200:201]
	s_nop 0
	v_pk_fma_f32 v[122:123], v[122:123], v[126:127], v[198:199]
	v_pk_fma_f32 v[120:121], v[120:121], v[124:125], v[196:197]
	global_store_dwordx4 v[140:141], v[136:139], off
; __device__ __forceinline__ unsigned pk2(float lo, float hi) { const f32x2 v = {lo, hi}; return __builtin_bit_cast(unsigned, __builtin_convertvector(v, bf16x2_t)); }
;     __device__ __forceinline__ void operator()(const f32x4 (&acc)[2][2][4][2], const Unit& un, int wr, int wc, int fr_, int fq_) const {
;     ...
; #pragma unroll
;             for (int m = 0; m < 4; ++m)
; #pragma unroll
;                 for (int bj = 0; bj < 2; ++bj) { const int row = rbase + ai * 128 + m * 16, col = cw + bj * 128; const f32x4 v0 = acc[ai][bj][m][0], v1 = acc[ai][bj][m][1];
;                     float* dp = dst + (size_t)(row - radj) * D + col;
;                     const f32x4 x0 = xa[m][bj][0] + g0[bj] * v0, x1 = xa[m][bj][1] + g1[bj] * v1;
;                     *(f32x4*)dp = x0; *(f32x4*)(dp + 4) = x1;
;                     ssq[ai][m] += (x0.x * x0.x + x0.y * x0.y) + (x0.z * x0.z + x0.w * x0.w) + (x1.x * x1.x + x1.y * x1.y) + (x1.z * x1.z + x1.w * x1.w);
;                     const f32x4 y0 = x0 * y0s[bj], y1 = x1 * y1s[bj];
;                     u32x4 w; w.x = pk2(y0.x, y0.y); w.y = pk2(y0.z, y0.w); w.z = pk2(y1.x, y1.y); w.w = pk2(y1.z, y1.w); *(u32x4*)(xg + (size_t)row * D + col) = w; } }
	v_pk_fma_f32 v[112:113], v[112:113], v[116:117], v[192:193]
	v_pk_fma_f32 v[114:115], v[114:115], v[118:119], v[194:195]
	v_mul_f32_e32 v136, v121, v121
	v_mul_f32_e32 v137, v123, v123
	v_fmac_f32_e32 v136, v120, v120
	v_fmac_f32_e32 v137, v122, v122
	v_add_f32_e32 v136, v136, v137
	v_mul_f32_e32 v137, v113, v113
	v_fmac_f32_e32 v137, v112, v112
	v_add_f32_e32 v136, v136, v137
	v_mul_f32_e32 v137, v115, v115
	v_fmac_f32_e32 v137, v114, v114
	v_add_f32_e32 v136, v137, v136
	global_store_dwordx4 v[212:213], v[120:123], off offset:512
	global_store_dwordx4 v[212:213], v[112:115], off offset:528
	v_add_f32_e32 v194, v202, v136
	v_pk_mul_f32 v[122:123], v[226:227], v[122:123]
	v_pk_mul_f32 v[120:121], v[228:229], v[120:121]
	v_pk_mul_f32 v[136:137], v[230:231], v[114:115]
	v_pk_mul_f32 v[114:115], v[232:233], v[112:113]
	v_cvt_pk_bf16_f32 v112, v120, v121
	v_cvt_pk_bf16_f32 v113, v122, v123
	v_cvt_pk_bf16_f32 v114, v114, v115
	v_cvt_pk_bf16_f32 v115, v136, v137
	v_or_b32_e32 v192, 16, v224
	global_store_dwordx4 v[140:141], v[112:115], off offset:256
	v_ashrrev_i32_e32 v193, 31, v192
	v_lshlrev_b64 v[120:121], 12, v[192:193]
	v_subrev_u32_e32 v112, s29, v192
	v_ashrrev_i32_e32 v113, 31, v112
	v_lshlrev_b64 v[112:113], 13, v[112:113]
	v_lshl_add_u64 v[112:113], s[42:43], 0, v[112:113]
	s_nop 0
	v_pk_fma_f32 v[110:111], v[110:111], v[134:135], v[190:191]
	v_pk_fma_f32 v[108:109], v[108:109], v[132:133], v[188:189]
	v_pk_fma_f32 v[106:107], v[106:107], v[130:131], v[186:187]
	v_pk_fma_f32 v[104:105], v[104:105], v[128:129], v[184:185]
	v_lshl_add_u64 v[122:123], v[112:113], 0, v[242:243]
	v_pk_mul_f32 v[114:115], v[234:235], v[110:111]
	v_pk_mul_f32 v[112:113], v[236:237], v[108:109]
	v_pk_mul_f32 v[136:137], v[238:239], v[106:107]
	v_pk_mul_f32 v[138:139], v[240:241], v[104:105]
	v_lshl_add_u64 v[120:121], s[20:21], 0, v[120:121]
	v_cvt_pk_bf16_f32 v112, v112, v113
	v_cvt_pk_bf16_f32 v113, v114, v115
	v_cvt_pk_bf16_f32 v114, v138, v139
	v_cvt_pk_bf16_f32 v115, v136, v137
	v_lshl_add_u64 v[120:121], v[120:121], 0, v[200:201]
	s_nop 0
	v_pk_fma_f32 v[102:103], v[102:103], v[126:127], v[182:183]
	v_pk_fma_f32 v[100:101], v[100:101], v[124:125], v[180:181]
	v_pk_fma_f32 v[98:99], v[98:99], v[118:119], v[178:179]
	v_pk_fma_f32 v[96:97], v[96:97], v[116:117], v[176:177]
	global_store_dwordx4 v[122:123], v[108:111], off
	global_store_dwordx4 v[122:123], v[104:107], off offset:16
	global_store_dwordx4 v[120:121], v[112:115], off
	global_store_dwordx4 v[122:123], v[100:103], off offset:512
	global_store_dwordx4 v[122:123], v[96:99], off offset:528
	v_pk_mul_f32 v[114:115], v[226:227], v[102:103]
	v_pk_mul_f32 v[112:113], v[228:229], v[100:101]
	v_pk_mul_f32 v[122:123], v[230:231], v[98:99]
	v_pk_mul_f32 v[136:137], v[232:233], v[96:97]
	v_cvt_pk_bf16_f32 v112, v112, v113
	v_cvt_pk_bf16_f32 v113, v114, v115
	v_cvt_pk_bf16_f32 v114, v136, v137
	v_cvt_pk_bf16_f32 v115, v122, v123
	v_or_b32_e32 v176, 32, v224
	global_store_dwordx4 v[120:121], v[112:115], off offset:256
	v_ashrrev_i32_e32 v177, 31, v176
	v_lshlrev_b64 v[120:121], 12, v[176:177]
	v_subrev_u32_e32 v112, s29, v176
	v_ashrrev_i32_e32 v113, 31, v112
	v_lshlrev_b64 v[112:113], 13, v[112:113]
	v_lshl_add_u64 v[112:113], s[42:43], 0, v[112:113]
	s_nop 0
	v_pk_fma_f32 v[94:95], v[94:95], v[134:135], v[174:175]
	v_pk_fma_f32 v[92:93], v[92:93], v[132:133], v[172:173]
	v_pk_fma_f32 v[90:91], v[90:91], v[130:131], v[170:171]
	v_pk_fma_f32 v[88:89], v[88:89], v[128:129], v[168:169]
	v_lshl_add_u64 v[122:123], v[112:113], 0, v[242:243]
	v_pk_mul_f32 v[114:115], v[234:235], v[94:95]
	v_pk_mul_f32 v[112:113], v[236:237], v[92:93]
	v_pk_mul_f32 v[136:137], v[238:239], v[90:91]
	v_pk_mul_f32 v[138:139], v[240:241], v[88:89]
	v_lshl_add_u64 v[120:121], s[20:21], 0, v[120:121]
	v_cvt_pk_bf16_f32 v112, v112, v113
	v_cvt_pk_bf16_f32 v113, v114, v115
	v_cvt_pk_bf16_f32 v114, v138, v139
	v_cvt_pk_bf16_f32 v115, v136, v137
	v_lshl_add_u64 v[120:121], v[120:121], 0, v[200:201]
	s_nop 0
	v_pk_fma_f32 v[86:87], v[86:87], v[126:127], v[166:167]
	v_pk_fma_f32 v[84:85], v[84:85], v[124:125], v[164:165]
	v_pk_fma_f32 v[82:83], v[82:83], v[118:119], v[162:163]
	v_pk_fma_f32 v[80:81], v[80:81], v[116:117], v[160:161]
	global_store_dwordx4 v[122:123], v[92:95], off
	global_store_dwordx4 v[122:123], v[88:91], off offset:16
	global_store_dwordx4 v[120:121], v[112:115], off
	global_store_dwordx4 v[122:123], v[84:87], off offset:512
	global_store_dwordx4 v[122:123], v[80:83], off offset:528
	v_pk_mul_f32 v[114:115], v[226:227], v[86:87]
	v_pk_mul_f32 v[112:113], v[228:229], v[84:85]
	v_pk_mul_f32 v[122:123], v[230:231], v[82:83]
	v_pk_mul_f32 v[136:137], v[232:233], v[80:81]
	v_cvt_pk_bf16_f32 v112, v112, v113
	v_cvt_pk_bf16_f32 v113, v114, v115
	v_cvt_pk_bf16_f32 v114, v136, v137
	v_cvt_pk_bf16_f32 v115, v122, v123
	v_or_b32_e32 v160, 48, v224
	global_store_dwordx4 v[120:121], v[112:115], off offset:256
	v_ashrrev_i32_e32 v161, 31, v160
	v_lshlrev_b64 v[120:121], 12, v[160:161]
	v_subrev_u32_e32 v112, s29, v160
	v_ashrrev_i32_e32 v113, 31, v112
	v_lshlrev_b64 v[112:113], 13, v[112:113]
	v_lshl_add_u64 v[112:113], s[42:43], 0, v[112:113]
	s_waitcnt vmcnt(20)
	v_pk_fma_f32 v[78:79], v[78:79], v[134:135], v[158:159]
	v_pk_fma_f32 v[76:77], v[76:77], v[132:133], v[156:157]
	v_pk_fma_f32 v[74:75], v[74:75], v[130:131], v[154:155]
	v_pk_fma_f32 v[72:73], v[72:73], v[128:129], v[152:153]
	v_lshl_add_u64 v[122:123], v[112:113], 0, v[242:243]
	v_pk_mul_f32 v[114:115], v[234:235], v[78:79]
	v_pk_mul_f32 v[112:113], v[236:237], v[76:77]
	v_pk_mul_f32 v[136:137], v[238:239], v[74:75]
	v_pk_mul_f32 v[138:139], v[240:241], v[72:73]
	v_lshl_add_u64 v[120:121], s[20:21], 0, v[120:121]
	v_cvt_pk_bf16_f32 v112, v112, v113
	v_cvt_pk_bf16_f32 v113, v114, v115
	v_cvt_pk_bf16_f32 v114, v138, v139
	v_cvt_pk_bf16_f32 v115, v136, v137
	v_lshl_add_u64 v[120:121], v[120:121], 0, v[200:201]
	s_waitcnt vmcnt(18)
; __device__ __forceinline__ unsigned pk2(float lo, float hi) { const f32x2 v = {lo, hi}; return __builtin_bit_cast(unsigned, __builtin_convertvector(v, bf16x2_t)); }
;     __device__ __forceinline__ void operator()(const f32x4 (&acc)[2][2][4][2], const Unit& un, int wr, int wc, int fr_, int fq_) const {
;     ...
;         for (int ai = 0; ai < 2; ++ai) {
;             f32x4 xa[4][2][2];
; #pragma unroll
;             for (int m = 0; m < 4; ++m)
; #pragma unroll
;                 for (int bj = 0; bj < 2; ++bj) { const float* sp = src + (size_t)(rbase + ai * 128 + m * 16 - radj) * D + cw + bj * 128; xa[m][bj][0] = *(const f32x4*)sp; xa[m][bj][1] = *(const f32x4*)(sp + 4); }
; #pragma unroll
;             for (int m = 0; m < 4; ++m)
; #pragma unroll
;                 for (int bj = 0; bj < 2; ++bj) { const int row = rbase + ai * 128 + m * 16, col = cw + bj * 128; const f32x4 v0 = acc[ai][bj][m][0], v1 = acc[ai][bj][m][1];
;                     float* dp = dst + (size_t)(row - radj) * D + col;
;                     const f32x4 x0 = xa[m][bj][0] + g0[bj] * v0, x1 = xa[m][bj][1] + g1[bj] * v1;
;                     *(f32x4*)dp = x0; *(f32x4*)(dp + 4) = x1;
;                     ssq[ai][m] += (x0.x * x0.x + x0.y * x0.y) + (x0.z * x0.z + x0.w * x0.w) + (x1.x * x1.x + x1.y * x1.y) + (x1.z * x1.z + x1.w * x1.w);
;                     const f32x4 y0 = x0 * y0s[bj], y1 = x1 * y1s[bj];
;                     u32x4 w; w.x = pk2(y0.x, y0.y); w.y = pk2(y0.z, y0.w); w.z = pk2(y1.x, y1.y); w.w = pk2(y1.z, y1.w); *(u32x4*)(xg + (size_t)row * D + col) = w; } }
	v_pk_fma_f32 v[70:71], v[70:71], v[126:127], v[150:151]
	v_pk_fma_f32 v[68:69], v[68:69], v[124:125], v[148:149]
	v_pk_fma_f32 v[66:67], v[66:67], v[118:119], v[146:147]
	v_pk_fma_f32 v[64:65], v[64:65], v[116:117], v[144:145]
	global_store_dwordx4 v[122:123], v[76:79], off
	global_store_dwordx4 v[122:123], v[72:75], off offset:16
	global_store_dwordx4 v[120:121], v[112:115], off
	global_store_dwordx4 v[122:123], v[68:71], off offset:512
	global_store_dwordx4 v[122:123], v[64:67], off offset:528
	v_pk_mul_f32 v[114:115], v[226:227], v[70:71]
	v_pk_mul_f32 v[112:113], v[228:229], v[68:69]
	v_pk_mul_f32 v[122:123], v[230:231], v[66:67]
	v_pk_mul_f32 v[136:137], v[232:233], v[64:65]
	v_cvt_pk_bf16_f32 v112, v112, v113
	v_cvt_pk_bf16_f32 v113, v114, v115
	v_cvt_pk_bf16_f32 v114, v136, v137
	v_cvt_pk_bf16_f32 v115, v122, v123
	global_store_dwordx4 v[120:121], v[112:115], off offset:256
	v_add_u32_e32 v144, 0x80, v224
	v_subrev_u32_e32 v158, s29, v144
	v_add_u32_e32 v112, 0x80, v246
	v_ashrrev_i32_e32 v113, 31, v112
	v_lshlrev_b64 v[112:113], 13, v[112:113]
	v_lshl_add_u64 v[112:113], v[244:245], 0, v[112:113]
	global_load_dwordx4 v[146:149], v[112:113], off offset:16 nt
	global_load_dwordx4 v[150:153], v[112:113], off nt
	global_load_dwordx4 v[154:157], v[112:113], off offset:528 nt
	global_load_dwordx4 v[162:165], v[112:113], off offset:512 nt
	v_add_u32_e32 v112, 0x90, v246
	v_ashrrev_i32_e32 v113, 31, v112
	v_lshlrev_b64 v[112:113], 13, v[112:113]
	v_lshl_add_u64 v[112:113], v[244:245], 0, v[112:113]
	global_load_dwordx4 v[166:169], v[112:113], off offset:16 nt
	global_load_dwordx4 v[170:173], v[112:113], off nt
	global_load_dwordx4 v[178:181], v[112:113], off offset:528 nt
	global_load_dwordx4 v[182:185], v[112:113], off offset:512 nt
	v_add_u32_e32 v112, 0xa0, v246
	v_ashrrev_i32_e32 v113, 31, v112
	v_lshlrev_b64 v[112:113], 13, v[112:113]
	v_lshl_add_u64 v[112:113], v[244:245], 0, v[112:113]
	global_load_dwordx4 v[186:189], v[112:113], off offset:16 nt
	global_load_dwordx4 v[196:199], v[112:113], off nt
	global_load_dwordx4 v[202:205], v[112:113], off offset:528 nt
	global_load_dwordx4 v[248:251], v[112:113], off offset:512 nt
	v_add_u32_e32 v112, 0xb0, v246
	v_ashrrev_i32_e32 v113, 31, v112
	v_lshlrev_b64 v[112:113], 13, v[112:113]
	v_lshl_add_u64 v[120:121], v[244:245], 0, v[112:113]
	global_load_dwordx4 v[136:139], v[120:121], off offset:16 nt
	global_load_dwordx4 v[140:143], v[120:121], off nt
	global_load_dwordx4 v[112:115], v[120:121], off offset:528 nt
	s_nop 0
	global_load_dwordx4 v[120:123], v[120:121], off offset:512 nt
	v_ashrrev_i32_e32 v159, 31, v158
	v_ashrrev_i32_e32 v145, 31, v144
	v_lshlrev_b64 v[158:159], 13, v[158:159]
	v_lshlrev_b64 v[174:175], 12, v[144:145]
	v_lshl_add_u64 v[158:159], s[42:43], 0, v[158:159]
	v_lshl_add_u64 v[158:159], v[158:159], 0, v[242:243]
	s_waitcnt vmcnt(15)
	v_pk_fma_f32 v[58:59], v[58:59], v[130:131], v[148:149]
	s_waitcnt vmcnt(14)
	v_pk_fma_f32 v[62:63], v[62:63], v[134:135], v[152:153]
	v_pk_fma_f32 v[60:61], v[60:61], v[132:133], v[150:151]
	v_pk_fma_f32 v[56:57], v[56:57], v[128:129], v[146:147]
	v_pk_mul_f32 v[148:149], v[234:235], v[62:63]
	v_pk_mul_f32 v[146:147], v[236:237], v[60:61]
	v_pk_mul_f32 v[150:151], v[238:239], v[58:59]
	v_pk_mul_f32 v[152:153], v[240:241], v[56:57]
	v_cvt_pk_bf16_f32 v146, v146, v147
	v_cvt_pk_bf16_f32 v147, v148, v149
	v_cvt_pk_bf16_f32 v149, v150, v151
	v_lshl_add_u64 v[150:151], s[20:21], 0, v[174:175]
	v_cvt_pk_bf16_f32 v148, v152, v153
	v_lshl_add_u64 v[150:151], v[150:151], 0, v[200:201]
	s_waitcnt vmcnt(12)
	v_pk_fma_f32 v[54:55], v[54:55], v[126:127], v[164:165]
	v_pk_fma_f32 v[52:53], v[52:53], v[124:125], v[162:163]
	v_pk_fma_f32 v[50:51], v[50:51], v[118:119], v[156:157]
	v_pk_fma_f32 v[48:49], v[48:49], v[116:117], v[154:155]
	global_store_dwordx4 v[158:159], v[60:63], off
	global_store_dwordx4 v[158:159], v[56:59], off offset:16
	global_store_dwordx4 v[150:151], v[146:149], off
	v_pk_mul_f32 v[152:153], v[230:231], v[50:51]
	v_pk_mul_f32 v[154:155], v[232:233], v[48:49]
	v_pk_mul_f32 v[148:149], v[226:227], v[54:55]
	v_pk_mul_f32 v[146:147], v[228:229], v[52:53]
	global_store_dwordx4 v[158:159], v[52:55], off offset:512
	global_store_dwordx4 v[158:159], v[48:51], off offset:528
	v_cvt_pk_bf16_f32 v146, v146, v147
	v_cvt_pk_bf16_f32 v147, v148, v149
	v_cvt_pk_bf16_f32 v148, v154, v155
	v_cvt_pk_bf16_f32 v149, v152, v153
	global_store_dwordx4 v[150:151], v[146:149], off offset:256
	s_waitcnt vmcnt(16)
	v_pk_fma_f32 v[46:47], v[46:47], v[134:135], v[172:173]
	v_pk_fma_f32 v[44:45], v[44:45], v[132:133], v[170:171]
	v_add_u32_e32 v146, 0x90, v224
	v_subrev_u32_e32 v148, s29, v146
	v_ashrrev_i32_e32 v149, 31, v148
	v_lshlrev_b64 v[148:149], 13, v[148:149]
	v_ashrrev_i32_e32 v147, 31, v146
	v_lshl_add_u64 v[148:149], s[42:43], 0, v[148:149]
	v_lshlrev_b64 v[152:153], 12, v[146:147]
	v_pk_fma_f32 v[42:43], v[42:43], v[130:131], v[168:169]
	v_pk_fma_f32 v[40:41], v[40:41], v[128:129], v[166:167]
	v_lshl_add_u64 v[154:155], v[148:149], 0, v[242:243]
	v_pk_mul_f32 v[150:151], v[234:235], v[46:47]
	v_pk_mul_f32 v[148:149], v[236:237], v[44:45]
	v_pk_mul_f32 v[156:157], v[238:239], v[42:43]
	v_pk_mul_f32 v[158:159], v[240:241], v[40:41]
	v_lshl_add_u64 v[152:153], s[20:21], 0, v[152:153]
	v_cvt_pk_bf16_f32 v148, v148, v149
	v_cvt_pk_bf16_f32 v149, v150, v151
	v_cvt_pk_bf16_f32 v150, v158, v159
	v_cvt_pk_bf16_f32 v151, v156, v157
	v_lshl_add_u64 v[152:153], v[152:153], 0, v[200:201]
	s_waitcnt vmcnt(14)
; __device__ __forceinline__ unsigned pk2(float lo, float hi) { const f32x2 v = {lo, hi}; return __builtin_bit_cast(unsigned, __builtin_convertvector(v, bf16x2_t)); }
;     __device__ __forceinline__ void operator()(const f32x4 (&acc)[2][2][4][2], const Unit& un, int wr, int wc, int fr_, int fq_) const {
;     ...
; #pragma unroll
;             for (int m = 0; m < 4; ++m)
; #pragma unroll
;                 for (int bj = 0; bj < 2; ++bj) { const int row = rbase + ai * 128 + m * 16, col = cw + bj * 128; const f32x4 v0 = acc[ai][bj][m][0], v1 = acc[ai][bj][m][1];
;                     float* dp = dst + (size_t)(row - radj) * D + col;
;                     const f32x4 x0 = xa[m][bj][0] + g0[bj] * v0, x1 = xa[m][bj][1] + g1[bj] * v1;
;                     *(f32x4*)dp = x0; *(f32x4*)(dp + 4) = x1;
;                     ssq[ai][m] += (x0.x * x0.x + x0.y * x0.y) + (x0.z * x0.z + x0.w * x0.w) + (x1.x * x1.x + x1.y * x1.y) + (x1.z * x1.z + x1.w * x1.w);
;                     const f32x4 y0 = x0 * y0s[bj], y1 = x1 * y1s[bj];
;                     u32x4 w; w.x = pk2(y0.x, y0.y); w.y = pk2(y0.z, y0.w); w.z = pk2(y1.x, y1.y); w.w = pk2(y1.z, y1.w); *(u32x4*)(xg + (size_t)row * D + col) = w; } }
; #pragma unroll
;         for (int ai = 0; ai < 2; ++ai)
; #pragma unroll
;             for (int m = 0; m < 4; ++m) { float s = ssq[ai][m]; s += shx<16>(s); s += shx<32>(s);
;                 if (fq == 0) ps[((size_t)(rbase + ai * 128 + m * 16) * 8 + un.pn) * 4 + wc] = s; }
	v_pk_fma_f32 v[38:39], v[38:39], v[126:127], v[184:185]
	v_pk_fma_f32 v[36:37], v[36:37], v[124:125], v[182:183]
	v_pk_fma_f32 v[34:35], v[34:35], v[118:119], v[180:181]
	v_pk_fma_f32 v[32:33], v[32:33], v[116:117], v[178:179]
	global_store_dwordx4 v[154:155], v[44:47], off
	global_store_dwordx4 v[154:155], v[40:43], off offset:16
	global_store_dwordx4 v[152:153], v[148:151], off
	global_store_dwordx4 v[154:155], v[36:39], off offset:512
	global_store_dwordx4 v[154:155], v[32:35], off offset:528
	v_pk_mul_f32 v[150:151], v[226:227], v[38:39]
	v_pk_mul_f32 v[148:149], v[228:229], v[36:37]
	v_pk_mul_f32 v[154:155], v[230:231], v[34:35]
	v_pk_mul_f32 v[156:157], v[232:233], v[32:33]
	v_cvt_pk_bf16_f32 v148, v148, v149
	v_cvt_pk_bf16_f32 v149, v150, v151
	v_cvt_pk_bf16_f32 v150, v156, v157
	v_cvt_pk_bf16_f32 v151, v154, v155
	global_store_dwordx4 v[152:153], v[148:151], off offset:256
	s_waitcnt vmcnt(18)
	v_pk_fma_f32 v[30:31], v[30:31], v[134:135], v[198:199]
	v_pk_fma_f32 v[28:29], v[28:29], v[132:133], v[196:197]
	v_add_u32_e32 v148, 0xa0, v224
	v_subrev_u32_e32 v150, s29, v148
	v_ashrrev_i32_e32 v151, 31, v150
	v_lshlrev_b64 v[150:151], 13, v[150:151]
	v_ashrrev_i32_e32 v149, 31, v148
	v_lshl_add_u64 v[150:151], s[42:43], 0, v[150:151]
	v_lshlrev_b64 v[154:155], 12, v[148:149]
	v_pk_fma_f32 v[26:27], v[26:27], v[130:131], v[188:189]
	v_pk_fma_f32 v[24:25], v[24:25], v[128:129], v[186:187]
	v_lshl_add_u64 v[156:157], v[150:151], 0, v[242:243]
	v_pk_mul_f32 v[152:153], v[234:235], v[30:31]
	v_pk_mul_f32 v[150:151], v[236:237], v[28:29]
	v_pk_mul_f32 v[158:159], v[238:239], v[26:27]
	v_pk_mul_f32 v[162:163], v[240:241], v[24:25]
	v_lshl_add_u64 v[154:155], s[20:21], 0, v[154:155]
	v_cvt_pk_bf16_f32 v150, v150, v151
	v_cvt_pk_bf16_f32 v151, v152, v153
	v_cvt_pk_bf16_f32 v152, v162, v163
	v_cvt_pk_bf16_f32 v153, v158, v159
	v_lshl_add_u64 v[154:155], v[154:155], 0, v[200:201]
	s_waitcnt vmcnt(16)
	v_pk_fma_f32 v[22:23], v[22:23], v[126:127], v[250:251]
	v_pk_fma_f32 v[20:21], v[20:21], v[124:125], v[248:249]
	v_pk_fma_f32 v[18:19], v[18:19], v[118:119], v[204:205]
	v_pk_fma_f32 v[16:17], v[16:17], v[116:117], v[202:203]
	global_store_dwordx4 v[156:157], v[28:31], off
	global_store_dwordx4 v[156:157], v[24:27], off offset:16
	global_store_dwordx4 v[154:155], v[150:153], off
	global_store_dwordx4 v[156:157], v[20:23], off offset:512
	global_store_dwordx4 v[156:157], v[16:19], off offset:528
	v_pk_mul_f32 v[152:153], v[226:227], v[22:23]
	v_pk_mul_f32 v[150:151], v[228:229], v[20:21]
	v_pk_mul_f32 v[156:157], v[230:231], v[18:19]
	v_pk_mul_f32 v[158:159], v[232:233], v[16:17]
	v_cvt_pk_bf16_f32 v150, v150, v151
	v_cvt_pk_bf16_f32 v151, v152, v153
	v_cvt_pk_bf16_f32 v152, v158, v159
	v_cvt_pk_bf16_f32 v153, v156, v157
	global_store_dwordx4 v[154:155], v[150:153], off offset:256
	s_waitcnt vmcnt(20)
	v_pk_fma_f32 v[14:15], v[14:15], v[134:135], v[142:143]
	v_pk_fma_f32 v[12:13], v[12:13], v[132:133], v[140:141]
	v_add_u32_e32 v150, 0xb0, v224
	v_subrev_u32_e32 v152, s29, v150
	v_ashrrev_i32_e32 v153, 31, v152
	v_ashrrev_i32_e32 v151, 31, v150
	v_pk_fma_f32 v[10:11], v[10:11], v[130:131], v[138:139]
	v_lshlrev_b64 v[152:153], 13, v[152:153]
	v_lshlrev_b64 v[154:155], 12, v[150:151]
	v_pk_fma_f32 v[8:9], v[8:9], v[128:129], v[136:137]
	v_pk_mul_f32 v[130:131], v[234:235], v[14:15]
	v_pk_mul_f32 v[128:129], v[236:237], v[12:13]
	v_pk_mul_f32 v[132:133], v[238:239], v[10:11]
	s_waitcnt vmcnt(18)
	v_pk_fma_f32 v[6:7], v[6:7], v[126:127], v[122:123]
	v_pk_fma_f32 v[4:5], v[4:5], v[124:125], v[120:121]
	v_pk_fma_f32 v[2:3], v[2:3], v[118:119], v[114:115]
	v_pk_fma_f32 v[0:1], v[0:1], v[116:117], v[112:113]
	v_lshl_add_u64 v[152:153], s[42:43], 0, v[152:153]
	v_pk_mul_f32 v[134:135], v[240:241], v[8:9]
	v_cvt_pk_bf16_f32 v128, v128, v129
	v_cvt_pk_bf16_f32 v129, v130, v131
	v_cvt_pk_bf16_f32 v131, v132, v133
	v_lshl_add_u64 v[132:133], s[20:21], 0, v[154:155]
	v_pk_mul_f32 v[114:115], v[226:227], v[6:7]
	v_pk_mul_f32 v[112:113], v[228:229], v[4:5]
	v_pk_mul_f32 v[116:117], v[230:231], v[2:3]
	v_pk_mul_f32 v[118:119], v[232:233], v[0:1]
	v_lshl_add_u64 v[152:153], v[152:153], 0, v[242:243]
	v_cvt_pk_bf16_f32 v130, v134, v135
	v_lshl_add_u64 v[132:133], v[132:133], 0, v[200:201]
	v_cvt_pk_bf16_f32 v112, v112, v113
	v_cvt_pk_bf16_f32 v113, v114, v115
	v_cvt_pk_bf16_f32 v114, v118, v119
	v_cvt_pk_bf16_f32 v115, v116, v117
	global_store_dwordx4 v[152:153], v[12:15], off
	global_store_dwordx4 v[152:153], v[8:11], off offset:16
	global_store_dwordx4 v[132:133], v[128:131], off
	global_store_dwordx4 v[152:153], v[4:7], off offset:512
	global_store_dwordx4 v[152:153], v[0:3], off offset:528
	global_store_dwordx4 v[132:133], v[112:115], off offset:256
	ds_swizzle_b32 v112, v194 offset:swizzle(SWAP,16)
	s_nop 0
	v_mbcnt_lo_u32_b32 v113, -1, 0
	v_mbcnt_hi_u32_b32 v113, -1, v113
	s_waitcnt lgkmcnt(0)
	v_add_f32_e32 v112, v194, v112
	v_lshlrev_b32_e32 v113, 2, v113
	v_xor_b32_e32 v113, 0x80, v113
	ds_bpermute_b32 v113, v113, v112
	s_and_saveexec_b64 s[40:41], vcc
	s_mov_b32 s74, 0x240000
	s_cbranch_execz .LBB0_1567
	v_lshlrev_b64 v[114:115], 7, v[224:225]
	v_lshl_add_u64 v[114:115], s[24:25], 0, v[114:115]
	v_lshl_add_u64 v[114:115], v[114:115], 0, s[38:39]
	s_mov_b32 s43, s91
	s_lshl_b32 s42, s63, 2
	v_lshl_add_u64 v[114:115], v[114:115], 0, s[42:43]
	s_waitcnt lgkmcnt(0)
	v_add_f32_e32 v112, v112, v113
	global_store_dword v[114:115], v112, off
